# phase 4 sample-unit epilogue: gate loads batched (16 in flight) instead of serial load-wait-store chain
# speedup vs baseline: 1.0083x; 1.0067x over previous
.LBB0_431:
	v_lshl_or_b32 v146, s72, 8, v170
	s_mov_b64 s[6:7], -1
	s_cmp_lt_i32 s47, 64
	v_ashrrev_i32_e32 v147, 31, v146
	s_cbranch_scc1 .LBB0_434
	s_lshl_b32 s6, s47, 8
	s_add_i32 s6, s6, s16
	v_or_b32_e32 v174, s6, v166
	v_add_u32_e32 v164, 0xffffc000, v174
	v_lshrrev_b32_e32 v150, 2, v164
	v_or_b32_e32 v150, 8, v150
	v_mov_b64_e32 v[152:153], s[50:51]
	v_mad_i64_i32 v[152:153], s[8:9], v150, s41, v[152:153]
	v_lshlrev_b64 v[148:149], 2, v[146:147]
	v_lshl_add_u64 v[176:177], v[152:153], 0, v[148:149]
	s_ashr_i32 s93, s92, 31
	s_lshl_b64 s[8:9], s[92:93], 21
	s_add_u32 s68, s26, s8
	s_addc_u32 s69, s27, s9
	v_ashrrev_i32_e32 v165, 31, v164
	v_lshlrev_b64 v[164:165], 12, v[164:165]
	v_lshl_add_u64 v[164:165], s[68:69], 0, v[164:165]
	v_lshl_add_u64 v[164:165], v[164:165], 0, v[148:149]
	global_load_dwordx4 v[180:183], v[176:177], off
	global_load_dwordx4 v[184:187], v[176:177], off offset:16
	global_load_dwordx4 v[188:191], v[176:177], off offset:512
	global_load_dwordx4 v[192:195], v[176:177], off offset:528
	s_mov_b64 s[8:9], 0x24000
	v_lshl_add_u64 v[150:151], v[176:177], 0, s[8:9]
	global_load_dwordx4 v[196:199], v[150:151], off
	global_load_dwordx4 v[200:203], v[150:151], off offset:16
	global_load_dwordx4 v[204:207], v[150:151], off offset:512
	global_load_dwordx4 v[208:211], v[150:151], off offset:528
	s_mov_b64 s[8:9], 0x48000
	v_lshl_add_u64 v[150:151], v[176:177], 0, s[8:9]
	global_load_dwordx4 v[212:215], v[150:151], off
	global_load_dwordx4 v[216:219], v[150:151], off offset:16
	global_load_dwordx4 v[230:233], v[150:151], off offset:512
	global_load_dwordx4 v[234:237], v[150:151], off offset:528
	s_mov_b64 s[8:9], 0x6c000
	v_lshl_add_u64 v[150:151], v[176:177], 0, s[8:9]
	global_load_dwordx4 v[238:241], v[150:151], off
	global_load_dwordx4 v[242:245], v[150:151], off offset:16
	global_load_dwordx4 v[246:249], v[150:151], off offset:512
	global_load_dwordx4 v[250:253], v[150:151], off offset:528
	s_waitcnt vmcnt(12)
	v_pk_mul_f32 v[180:181], v[180:181], 0.5 op_sel_hi:[1,0]
	v_pk_mul_f32 v[182:183], v[182:183], 0.5 op_sel_hi:[1,0]
	v_pk_mul_f32 v[180:181], v[124:125], v[180:181]
	v_pk_mul_f32 v[182:183], v[126:127], v[182:183]
	v_pk_mul_f32 v[184:185], v[184:185], 0.5 op_sel_hi:[1,0]
	v_pk_mul_f32 v[186:187], v[186:187], 0.5 op_sel_hi:[1,0]
	v_pk_mul_f32 v[184:185], v[120:121], v[184:185]
	v_pk_mul_f32 v[186:187], v[122:123], v[186:187]
	v_pk_mul_f32 v[188:189], v[188:189], 0.5 op_sel_hi:[1,0]
	v_pk_mul_f32 v[190:191], v[190:191], 0.5 op_sel_hi:[1,0]
	v_pk_mul_f32 v[188:189], v[108:109], v[188:189]
	v_pk_mul_f32 v[190:191], v[110:111], v[190:191]
	v_pk_mul_f32 v[192:193], v[192:193], 0.5 op_sel_hi:[1,0]
	v_pk_mul_f32 v[194:195], v[194:195], 0.5 op_sel_hi:[1,0]
	v_pk_mul_f32 v[192:193], v[104:105], v[192:193]
	v_pk_mul_f32 v[194:195], v[106:107], v[194:195]
	global_store_dwordx4 v[164:165], v[180:183], off
	global_store_dwordx4 v[164:165], v[184:187], off offset:16
	global_store_dwordx4 v[164:165], v[188:191], off offset:512
	global_store_dwordx4 v[164:165], v[192:195], off offset:528
	s_mov_b64 s[8:9], 0x120000
	v_lshl_add_u64 v[150:151], v[176:177], 0, s[8:9]
	global_load_dwordx4 v[124:127], v[150:151], off
	global_load_dwordx4 v[120:123], v[150:151], off offset:16
	global_load_dwordx4 v[108:111], v[150:151], off offset:512
	global_load_dwordx4 v[104:107], v[150:151], off offset:528
	s_waitcnt vmcnt(16)
	v_pk_mul_f32 v[196:197], v[196:197], 0.5 op_sel_hi:[1,0]
	v_pk_mul_f32 v[198:199], v[198:199], 0.5 op_sel_hi:[1,0]
	v_pk_mul_f32 v[196:197], v[116:117], v[196:197]
	v_pk_mul_f32 v[198:199], v[118:119], v[198:199]
	v_pk_mul_f32 v[200:201], v[200:201], 0.5 op_sel_hi:[1,0]
	v_pk_mul_f32 v[202:203], v[202:203], 0.5 op_sel_hi:[1,0]
	v_pk_mul_f32 v[200:201], v[112:113], v[200:201]
	v_pk_mul_f32 v[202:203], v[114:115], v[202:203]
	v_pk_mul_f32 v[204:205], v[204:205], 0.5 op_sel_hi:[1,0]
	v_pk_mul_f32 v[206:207], v[206:207], 0.5 op_sel_hi:[1,0]
	v_pk_mul_f32 v[204:205], v[100:101], v[204:205]
	v_pk_mul_f32 v[206:207], v[102:103], v[206:207]
	v_pk_mul_f32 v[208:209], v[208:209], 0.5 op_sel_hi:[1,0]
	v_pk_mul_f32 v[210:211], v[210:211], 0.5 op_sel_hi:[1,0]
	v_pk_mul_f32 v[208:209], v[96:97], v[208:209]
	v_pk_mul_f32 v[210:211], v[98:99], v[210:211]
	s_mov_b64 s[8:9], 0x10000
	v_lshl_add_u64 v[152:153], v[164:165], 0, s[8:9]
	global_store_dwordx4 v[152:153], v[196:199], off
	global_store_dwordx4 v[152:153], v[200:203], off offset:16
	global_store_dwordx4 v[152:153], v[204:207], off offset:512
	global_store_dwordx4 v[152:153], v[208:211], off offset:528
	s_mov_b64 s[8:9], 0x144000
	v_lshl_add_u64 v[150:151], v[176:177], 0, s[8:9]
	global_load_dwordx4 v[116:119], v[150:151], off
	global_load_dwordx4 v[112:115], v[150:151], off offset:16
	global_load_dwordx4 v[100:103], v[150:151], off offset:512
	global_load_dwordx4 v[96:99], v[150:151], off offset:528
	s_waitcnt vmcnt(20)
	v_pk_mul_f32 v[212:213], v[212:213], 0.5 op_sel_hi:[1,0]
	v_pk_mul_f32 v[214:215], v[214:215], 0.5 op_sel_hi:[1,0]
	v_pk_mul_f32 v[212:213], v[92:93], v[212:213]
	v_pk_mul_f32 v[214:215], v[94:95], v[214:215]
	v_pk_mul_f32 v[216:217], v[216:217], 0.5 op_sel_hi:[1,0]
	v_pk_mul_f32 v[218:219], v[218:219], 0.5 op_sel_hi:[1,0]
	v_pk_mul_f32 v[216:217], v[88:89], v[216:217]
	v_pk_mul_f32 v[218:219], v[90:91], v[218:219]
	v_pk_mul_f32 v[230:231], v[230:231], 0.5 op_sel_hi:[1,0]
	v_pk_mul_f32 v[232:233], v[232:233], 0.5 op_sel_hi:[1,0]
	v_pk_mul_f32 v[230:231], v[76:77], v[230:231]
	v_pk_mul_f32 v[232:233], v[78:79], v[232:233]
	v_pk_mul_f32 v[234:235], v[234:235], 0.5 op_sel_hi:[1,0]
	v_pk_mul_f32 v[236:237], v[236:237], 0.5 op_sel_hi:[1,0]
	v_pk_mul_f32 v[234:235], v[72:73], v[234:235]
	v_pk_mul_f32 v[236:237], v[74:75], v[236:237]
	s_mov_b64 s[8:9], 0x20000
	v_lshl_add_u64 v[152:153], v[164:165], 0, s[8:9]
	global_store_dwordx4 v[152:153], v[212:215], off
	global_store_dwordx4 v[152:153], v[216:219], off offset:16
	global_store_dwordx4 v[152:153], v[230:233], off offset:512
	global_store_dwordx4 v[152:153], v[234:237], off offset:528
	s_mov_b64 s[8:9], 0x168000
	v_lshl_add_u64 v[150:151], v[176:177], 0, s[8:9]
	global_load_dwordx4 v[92:95], v[150:151], off
	global_load_dwordx4 v[88:91], v[150:151], off offset:16
	global_load_dwordx4 v[76:79], v[150:151], off offset:512
	global_load_dwordx4 v[72:75], v[150:151], off offset:528
	s_waitcnt vmcnt(24)
	v_pk_mul_f32 v[238:239], v[238:239], 0.5 op_sel_hi:[1,0]
	v_pk_mul_f32 v[240:241], v[240:241], 0.5 op_sel_hi:[1,0]
	v_pk_mul_f32 v[238:239], v[84:85], v[238:239]
	v_pk_mul_f32 v[240:241], v[86:87], v[240:241]
	v_pk_mul_f32 v[242:243], v[242:243], 0.5 op_sel_hi:[1,0]
	v_pk_mul_f32 v[244:245], v[244:245], 0.5 op_sel_hi:[1,0]
	v_pk_mul_f32 v[242:243], v[80:81], v[242:243]
	v_pk_mul_f32 v[244:245], v[82:83], v[244:245]
	v_pk_mul_f32 v[246:247], v[246:247], 0.5 op_sel_hi:[1,0]
	v_pk_mul_f32 v[248:249], v[248:249], 0.5 op_sel_hi:[1,0]
	v_pk_mul_f32 v[246:247], v[68:69], v[246:247]
	v_pk_mul_f32 v[248:249], v[70:71], v[248:249]
	v_pk_mul_f32 v[250:251], v[250:251], 0.5 op_sel_hi:[1,0]
	v_pk_mul_f32 v[252:253], v[252:253], 0.5 op_sel_hi:[1,0]
	v_pk_mul_f32 v[250:251], v[64:65], v[250:251]
	v_pk_mul_f32 v[252:253], v[66:67], v[252:253]
	s_mov_b64 s[8:9], 0x30000
	v_lshl_add_u64 v[152:153], v[164:165], 0, s[8:9]
	global_store_dwordx4 v[152:153], v[238:241], off
	global_store_dwordx4 v[152:153], v[242:245], off offset:16
	global_store_dwordx4 v[152:153], v[246:249], off offset:512
	global_store_dwordx4 v[152:153], v[250:253], off offset:528
	s_mov_b64 s[8:9], 0x18c000
	v_lshl_add_u64 v[150:151], v[176:177], 0, s[8:9]
	global_load_dwordx4 v[84:87], v[150:151], off
	global_load_dwordx4 v[80:83], v[150:151], off offset:16
	global_load_dwordx4 v[68:71], v[150:151], off offset:512
	global_load_dwordx4 v[64:67], v[150:151], off offset:528
	s_waitcnt vmcnt(24)
	v_pk_mul_f32 v[124:125], v[124:125], 0.5 op_sel_hi:[1,0]
	v_pk_mul_f32 v[126:127], v[126:127], 0.5 op_sel_hi:[1,0]
	v_pk_mul_f32 v[124:125], v[60:61], v[124:125]
	v_pk_mul_f32 v[126:127], v[62:63], v[126:127]
	v_pk_mul_f32 v[120:121], v[120:121], 0.5 op_sel_hi:[1,0]
	v_pk_mul_f32 v[122:123], v[122:123], 0.5 op_sel_hi:[1,0]
	v_pk_mul_f32 v[120:121], v[56:57], v[120:121]
	v_pk_mul_f32 v[122:123], v[58:59], v[122:123]
	v_pk_mul_f32 v[108:109], v[108:109], 0.5 op_sel_hi:[1,0]
	v_pk_mul_f32 v[110:111], v[110:111], 0.5 op_sel_hi:[1,0]
	v_pk_mul_f32 v[108:109], v[44:45], v[108:109]
	v_pk_mul_f32 v[110:111], v[46:47], v[110:111]
	v_pk_mul_f32 v[104:105], v[104:105], 0.5 op_sel_hi:[1,0]
	v_pk_mul_f32 v[106:107], v[106:107], 0.5 op_sel_hi:[1,0]
	v_pk_mul_f32 v[104:105], v[40:41], v[104:105]
	v_pk_mul_f32 v[106:107], v[42:43], v[106:107]
	s_mov_b64 s[8:9], 0x80000
	v_lshl_add_u64 v[152:153], v[164:165], 0, s[8:9]
	global_store_dwordx4 v[152:153], v[124:127], off
	global_store_dwordx4 v[152:153], v[120:123], off offset:16
	global_store_dwordx4 v[152:153], v[108:111], off offset:512
	global_store_dwordx4 v[152:153], v[104:107], off offset:528
	s_waitcnt vmcnt(20)
	v_pk_mul_f32 v[116:117], v[116:117], 0.5 op_sel_hi:[1,0]
	v_pk_mul_f32 v[118:119], v[118:119], 0.5 op_sel_hi:[1,0]
	v_pk_mul_f32 v[116:117], v[52:53], v[116:117]
	v_pk_mul_f32 v[118:119], v[54:55], v[118:119]
	v_pk_mul_f32 v[112:113], v[112:113], 0.5 op_sel_hi:[1,0]
	v_pk_mul_f32 v[114:115], v[114:115], 0.5 op_sel_hi:[1,0]
	v_pk_mul_f32 v[112:113], v[48:49], v[112:113]
	v_pk_mul_f32 v[114:115], v[50:51], v[114:115]
	v_pk_mul_f32 v[100:101], v[100:101], 0.5 op_sel_hi:[1,0]
	v_pk_mul_f32 v[102:103], v[102:103], 0.5 op_sel_hi:[1,0]
	v_pk_mul_f32 v[100:101], v[36:37], v[100:101]
	v_pk_mul_f32 v[102:103], v[38:39], v[102:103]
	v_pk_mul_f32 v[96:97], v[96:97], 0.5 op_sel_hi:[1,0]
	v_pk_mul_f32 v[98:99], v[98:99], 0.5 op_sel_hi:[1,0]
	v_pk_mul_f32 v[96:97], v[32:33], v[96:97]
	v_pk_mul_f32 v[98:99], v[34:35], v[98:99]
	s_mov_b64 s[8:9], 0x90000
	v_lshl_add_u64 v[152:153], v[164:165], 0, s[8:9]
	global_store_dwordx4 v[152:153], v[116:119], off
	global_store_dwordx4 v[152:153], v[112:115], off offset:16
	global_store_dwordx4 v[152:153], v[100:103], off offset:512
	global_store_dwordx4 v[152:153], v[96:99], off offset:528
	s_waitcnt vmcnt(16)
	v_pk_mul_f32 v[92:93], v[92:93], 0.5 op_sel_hi:[1,0]
	v_pk_mul_f32 v[94:95], v[94:95], 0.5 op_sel_hi:[1,0]
	v_pk_mul_f32 v[92:93], v[28:29], v[92:93]
	v_pk_mul_f32 v[94:95], v[30:31], v[94:95]
	v_pk_mul_f32 v[88:89], v[88:89], 0.5 op_sel_hi:[1,0]
	v_pk_mul_f32 v[90:91], v[90:91], 0.5 op_sel_hi:[1,0]
	v_pk_mul_f32 v[88:89], v[24:25], v[88:89]
	v_pk_mul_f32 v[90:91], v[26:27], v[90:91]
	v_pk_mul_f32 v[76:77], v[76:77], 0.5 op_sel_hi:[1,0]
	v_pk_mul_f32 v[78:79], v[78:79], 0.5 op_sel_hi:[1,0]
	v_pk_mul_f32 v[76:77], v[12:13], v[76:77]
	v_pk_mul_f32 v[78:79], v[14:15], v[78:79]
	v_pk_mul_f32 v[72:73], v[72:73], 0.5 op_sel_hi:[1,0]
	v_pk_mul_f32 v[74:75], v[74:75], 0.5 op_sel_hi:[1,0]
	v_pk_mul_f32 v[72:73], v[8:9], v[72:73]
	v_pk_mul_f32 v[74:75], v[10:11], v[74:75]
	s_mov_b64 s[8:9], 0xa0000
	v_lshl_add_u64 v[152:153], v[164:165], 0, s[8:9]
	global_store_dwordx4 v[152:153], v[92:95], off
	global_store_dwordx4 v[152:153], v[88:91], off offset:16
	global_store_dwordx4 v[152:153], v[76:79], off offset:512
	global_store_dwordx4 v[152:153], v[72:75], off offset:528
	s_waitcnt vmcnt(12)
	v_pk_mul_f32 v[84:85], v[84:85], 0.5 op_sel_hi:[1,0]
	v_pk_mul_f32 v[86:87], v[86:87], 0.5 op_sel_hi:[1,0]
	v_pk_mul_f32 v[84:85], v[20:21], v[84:85]
	v_pk_mul_f32 v[86:87], v[22:23], v[86:87]
	v_pk_mul_f32 v[80:81], v[80:81], 0.5 op_sel_hi:[1,0]
	v_pk_mul_f32 v[82:83], v[82:83], 0.5 op_sel_hi:[1,0]
	v_pk_mul_f32 v[80:81], v[16:17], v[80:81]
	v_pk_mul_f32 v[82:83], v[18:19], v[82:83]
	v_pk_mul_f32 v[68:69], v[68:69], 0.5 op_sel_hi:[1,0]
	v_pk_mul_f32 v[70:71], v[70:71], 0.5 op_sel_hi:[1,0]
	v_pk_mul_f32 v[68:69], v[4:5], v[68:69]
	v_pk_mul_f32 v[70:71], v[6:7], v[70:71]
	v_pk_mul_f32 v[64:65], v[64:65], 0.5 op_sel_hi:[1,0]
	v_pk_mul_f32 v[66:67], v[66:67], 0.5 op_sel_hi:[1,0]
	v_pk_mul_f32 v[64:65], v[0:1], v[64:65]
	v_pk_mul_f32 v[66:67], v[2:3], v[66:67]
	s_mov_b64 s[8:9], 0xb0000
	v_lshl_add_u64 v[152:153], v[164:165], 0, s[8:9]
	global_store_dwordx4 v[152:153], v[84:87], off
	global_store_dwordx4 v[152:153], v[80:83], off offset:16
	global_store_dwordx4 v[152:153], v[68:71], off offset:512
	global_store_dwordx4 v[152:153], v[64:67], off offset:528
	s_cbranch_execz .LBB0_435
